# window loop at s_setprio 2, selected-branch waves with work at 1
# baseline (speedup 1.0000x reference)
.LBB0_669:
	s_waitcnt lgkmcnt(0)
	v_mov_b32_e32 v162, 0
	s_cmp_lt_i32 s29, 0
	v_mov_b32_e32 v158, 0
	v_mov_b32_e32 v154, 0
	v_mov_b32_e32 v150, 0
	v_mov_b32_e32 v149, v162
	v_mov_b32_e32 v148, v162
	v_mov_b32_e32 v147, v162
	v_mov_b32_e32 v146, v162
	v_mov_b32_e32 v133, v162
	v_mov_b32_e32 v132, v162
	v_mov_b32_e32 v131, v162
	v_mov_b32_e32 v130, v162
	v_mov_b32_e32 v99, v162
	v_mov_b32_e32 v98, v162
	v_mov_b32_e32 v97, v162
	v_mov_b32_e32 v96, v162
	v_mov_b32_e32 v83, v162
	v_mov_b32_e32 v82, v162
	v_mov_b32_e32 v81, v162
	v_mov_b32_e32 v80, v162
	v_mov_b32_e32 v145, v162
	v_mov_b32_e32 v144, v162
	v_mov_b32_e32 v143, v162
	v_mov_b32_e32 v142, v162
	v_mov_b32_e32 v127, v162
	v_mov_b32_e32 v126, v162
	v_mov_b32_e32 v125, v162
	v_mov_b32_e32 v124, v162
	v_mov_b32_e32 v95, v162
	v_mov_b32_e32 v94, v162
	v_mov_b32_e32 v93, v162
	v_mov_b32_e32 v92, v162
	v_mov_b32_e32 v79, v162
	v_mov_b32_e32 v78, v162
	v_mov_b32_e32 v77, v162
	v_mov_b32_e32 v76, v162
	v_mov_b32_e32 v141, v162
	v_mov_b32_e32 v140, v162
	v_mov_b32_e32 v139, v162
	v_mov_b32_e32 v138, v162
	v_mov_b32_e32 v123, v162
	v_mov_b32_e32 v122, v162
	v_mov_b32_e32 v121, v162
	v_mov_b32_e32 v120, v162
	v_mov_b32_e32 v91, v162
	v_mov_b32_e32 v90, v162
	v_mov_b32_e32 v89, v162
	v_mov_b32_e32 v88, v162
	v_mov_b32_e32 v71, v162
	v_mov_b32_e32 v70, v162
	v_mov_b32_e32 v69, v162
	v_mov_b32_e32 v68, v162
	v_mov_b32_e32 v137, v162
	v_mov_b32_e32 v136, v162
	v_mov_b32_e32 v135, v162
	v_mov_b32_e32 v134, v162
	v_mov_b32_e32 v119, v162
	v_mov_b32_e32 v118, v162
	v_mov_b32_e32 v117, v162
	v_mov_b32_e32 v116, v162
	v_mov_b32_e32 v87, v162
	v_mov_b32_e32 v86, v162
	v_mov_b32_e32 v85, v162
	v_mov_b32_e32 v84, v162
	v_mov_b32_e32 v35, v162
	v_mov_b32_e32 v34, v162
	v_mov_b32_e32 v33, v162
	v_mov_b32_e32 v32, v162
	s_barrier
	s_cbranch_scc1 .LBB0_748
	v_and_b32_e32 v35, 12, v73
	s_movk_i32 s2, 0x1320
	v_lshrrev_b32_e32 v32, 4, v73
	v_lshrrev_b32_e64 v35, v35, s2
	v_xor_b32_e32 v32, v35, v32
	v_lshlrev_b32_e32 v34, 6, v101
	v_lshlrev_b32_e32 v32, 4, v32
	v_and_or_b32 v217, v32, 48, v34
	v_lshrrev_b32_e32 v32, 1, v101
	s_lshl_b32 s70, s40, 6
	s_lshl_b32 s2, s64, 6
	v_xor_b32_e32 v34, v32, v100
	v_bitop3_b32 v32, v100, v32, 4 bitop3:0x36
	s_add_i32 s2, s70, s2
	v_lshlrev_b32_e32 v35, 4, v32
	v_lshrrev_b32_e32 v32, 2, v101
	v_lshl_or_b32 v68, v100, 2, s2
	v_sub_u32_e32 v32, v68, v32
	v_lshlrev_b32_e32 v33, 7, v101
	v_lshlrev_b32_e32 v34, 4, v34
	v_sub_u32_e32 v242, v32, v240
	v_mov_b32_e32 v32, 0
	v_mov_b32_e32 v73, v72
	v_mov_b32_e32 v74, v72
	v_mov_b32_e32 v75, v72
	s_add_i32 s65, s41, 0xfffffe0f
	s_mov_b32 s71, 0
	v_add_u32_e32 v243, v33, v34
	v_add_u32_e32 v244, v33, v35
	s_mov_b32 s74, 0
	v_mov_b32_e32 v33, v32
	v_mov_b32_e32 v34, v32
	v_mov_b32_e32 v35, v32
	v_mov_b32_e32 v68, v32
	v_mov_b32_e32 v69, v32
	v_mov_b32_e32 v70, v32
	v_mov_b32_e32 v71, v32
	v_mov_b32_e32 v76, v32
	v_mov_b32_e32 v77, v32
	v_mov_b32_e32 v78, v32
	v_mov_b32_e32 v79, v32
	v_mov_b32_e32 v80, v32
	v_mov_b32_e32 v81, v32
	v_mov_b32_e32 v82, v32
	v_mov_b32_e32 v83, v32
	v_mov_b32_e32 v84, v32
	v_mov_b32_e32 v85, v32
	v_mov_b32_e32 v86, v32
	v_mov_b32_e32 v87, v32
	v_mov_b32_e32 v88, v32
	v_mov_b32_e32 v89, v32
	v_mov_b32_e32 v90, v32
	v_mov_b32_e32 v91, v32
	v_mov_b32_e32 v92, v32
	v_mov_b32_e32 v93, v32
	v_mov_b32_e32 v94, v32
	v_mov_b32_e32 v95, v32
	v_mov_b32_e32 v96, v32
	v_mov_b32_e32 v97, v32
	v_mov_b32_e32 v98, v32
	v_mov_b32_e32 v99, v32
	v_mov_b32_e32 v116, v32
	v_mov_b32_e32 v117, v32
	v_mov_b32_e32 v118, v32
	v_mov_b32_e32 v119, v32
	v_mov_b32_e32 v120, v32
	v_mov_b32_e32 v121, v32
	v_mov_b32_e32 v122, v32
	v_mov_b32_e32 v123, v32
	v_mov_b32_e32 v124, v32
	v_mov_b32_e32 v125, v32
	v_mov_b32_e32 v126, v32
	v_mov_b32_e32 v127, v32
	v_mov_b32_e32 v130, v32
	v_mov_b32_e32 v131, v32
	v_mov_b32_e32 v132, v32
	v_mov_b32_e32 v133, v32
	v_mov_b32_e32 v134, v32
	v_mov_b32_e32 v135, v32
	v_mov_b32_e32 v136, v32
	v_mov_b32_e32 v137, v32
	v_mov_b32_e32 v138, v32
	v_mov_b32_e32 v139, v32
	v_mov_b32_e32 v140, v32
	v_mov_b32_e32 v141, v32
	v_mov_b32_e32 v142, v32
	v_mov_b32_e32 v143, v32
	v_mov_b32_e32 v144, v32
	v_mov_b32_e32 v145, v32
	v_mov_b32_e32 v146, v32
	v_mov_b32_e32 v147, v32
	v_mov_b32_e32 v148, v32
	v_mov_b32_e32 v149, v32
	v_mov_b32_e32 v150, v32
	v_mov_b32_e32 v151, v32
	v_mov_b32_e32 v152, v32
	v_mov_b32_e32 v153, v32
	v_mov_b32_e32 v154, v32
	v_mov_b32_e32 v155, v32
	v_mov_b32_e32 v156, v32
	v_mov_b32_e32 v157, v32
	v_mov_b32_e32 v158, v32
	v_mov_b32_e32 v159, v32
	v_mov_b32_e32 v160, v32
	v_mov_b32_e32 v161, v32
	v_mov_b32_e32 v162, v32
	v_mov_b32_e32 v163, v32
	v_mov_b32_e32 v164, v32
	v_mov_b32_e32 v165, v32
	s_setprio 2
	s_cmp_lt_i32 s74, s29
	s_cselect_b64 s[46:47], -1, 0
	s_cmp_ge_i32 s74, s29
	s_cbranch_scc0 .LBB0_672
	s_branch .LBB0_673
